# grid barrier: non-leader workgroups poll the top-level generation word directly (one hop fewer); scan unit chunk prefetch; ret_sample state rows streamed 4 deep; gemm_small pipelined
# speedup vs baseline: 1.0191x; 1.0136x over previous
.LBB0_306:
	s_andn2_b64 vcc, exec, s[10:11]
	s_cbranch_vccnz .LBB0_281
	s_andn2_b64 vcc, exec, s[24:25]
	s_cbranch_vccnz .LBB0_281
	s_bfe_u32 s0, s68, 0x20002
	v_cvt_f32_ubyte0_e32 v0, s0
	v_sub_f32_e32 v0, 0xc0a00000, v0
	v_exp_f32_e32 v0, v0
	s_mov_b32 s4, 0x800000
	s_mov_b64 s[54:55], s[94:95]
	v_sub_f32_e32 v0, 1.0, v0
	v_cmp_gt_f32_e32 vcc, s4, v0
	s_and_b64 s[52:53], vcc, exec
	s_cselect_b32 s4, 32, 0
	v_ldexp_f32 v0, v0, s4
	v_log_f32_e32 v2, v0
	v_cndmask_b32_e32 v1, 0, v155, vcc
	s_lshl_b32 s5, s68, 2
	s_and_b32 s64, s68, 3
	v_sub_f32_e32 v1, v2, v1
	v_mul_f32_e32 v2, 0x43000000, v1
	s_andn2_b32 s5, s5, 63
	s_ashr_i32 s65, s68, 4
	v_exp_f32_e32 v16, v2
	v_lshl_add_u64 v[2:3], v[110:111], 1, s[54:55]
	s_lshl_b32 s4, s0, 8
	v_lshl_or_b32 v152, s64, 14, v173
	s_or_b32 s52, s5, s0
	v_lshl_add_u64 v[2:3], v[2:3], 0, v[152:153]
	s_mov_b64 s[12:13], 0x1d700000
	s_add_u32 s66, s54, 0xc701800
	v_lshl_add_u64 v[28:29], v[2:3], 0, s[12:13]
	s_addc_u32 s67, s55, 0
	s_mul_i32 s5, s65, 0x1400000
	s_lshl_b32 s12, s0, 9
	s_or_b32 s12, s5, s12
	s_lshl_b32 s13, s64, 7
	v_mul_f32_e32 v4, v1, v109
	s_or_b32 s84, s12, s13
	v_exp_f32_e32 v18, v4
	v_mul_f32_e32 v4, v1, v162
	v_lshl_add_u64 v[2:3], s[66:67], 0, v[120:121]
	s_mul_hi_i32 s85, s65, 0x1400000
	s_add_u32 s54, s54, 0xc701400
	v_exp_f32_e32 v20, v4
	v_mul_f32_e32 v4, v1, v163
	v_mul_f32_e32 v1, v1, v164
	v_lshl_add_u64 v[30:31], v[2:3], 0, s[84:85]
	v_lshl_add_u64 v[2:3], s[66:67], 0, v[122:123]
	s_addc_u32 s55, s55, 0
	v_exp_f32_e32 v22, v4
	v_exp_f32_e32 v24, v1
	v_lshl_add_u64 v[32:33], v[2:3], 0, s[84:85]
	v_lshl_add_u64 v[2:3], s[54:55], 0, v[124:125]
	s_or_b32 s84, s5, s4
	v_lshl_add_u64 v[34:35], v[2:3], 0, s[84:85]
	v_lshl_add_u64 v[2:3], s[54:55], 0, v[126:127]
	v_lshl_add_u64 v[36:37], v[2:3], 0, s[84:85]
	v_lshl_add_u64 v[2:3], s[54:55], 0, v[120:121]
	v_mov_b32_e32 v0, 0
	v_lshl_add_u64 v[38:39], v[2:3], 0, s[84:85]
	v_lshl_add_u64 v[2:3], s[54:55], 0, v[122:123]
	s_mov_b64 s[10:11], s[92:93]
	v_mov_b32_e32 v26, v16
	v_mov_b32_e32 v27, v16
	v_mov_b32_e32 v21, v20
	v_mov_b32_e32 v19, v18
	v_mov_b32_e32 v25, v24
	v_mov_b32_e32 v23, v22
	v_lshl_add_u64 v[40:41], v[2:3], 0, s[84:85]
	s_mov_b64 s[54:55], 0
	v_mov_b32_e32 v1, v0
	v_mov_b32_e32 v2, v0
	v_mov_b32_e32 v3, v0
	v_mov_b32_e32 v4, v0
	v_mov_b32_e32 v5, v0
	v_mov_b32_e32 v6, v0
	v_mov_b32_e32 v7, v0
	v_mov_b32_e32 v8, v0
	v_mov_b32_e32 v9, v0
	v_mov_b32_e32 v10, v0
	v_mov_b32_e32 v11, v0
	v_mov_b32_e32 v12, v0
	v_mov_b32_e32 v13, v0
	v_mov_b32_e32 v14, v0
	v_mov_b32_e32 v15, v0
	s_movk_i32 s4, 0x1000
	s_movk_i32 s5, 0x2000
	s_movk_i32 s12, 0x3000
	global_load_dwordx4 v[224:227], v[40:41], off
	global_load_dwordx4 v[228:231], v[38:39], off
	global_load_dwordx4 v[232:235], v[36:37], off
	global_load_dwordx4 v[236:239], v[34:35], off
	global_load_dwordx4 v[240:243], v[32:33], off
	global_load_dwordx4 v[244:247], v[30:31], off
.LBB0_309:
	s_ashr_i32 s53, s52, 31
	s_lshl_b64 s[66:67], s[52:53], 16
	v_lshl_add_u64 v[44:45], v[28:29], 0, s[66:67]
	v_cvt_pk_bf16_f32 v42, v0, v1
	v_cvt_pk_bf16_f32 v43, v2, v3
	v_add_co_u32_e32 v46, vcc, s4, v44
	global_store_dwordx2 v[44:45], v[42:43], off
	v_cvt_pk_bf16_f32 v42, v4, v5
	v_cvt_pk_bf16_f32 v43, v6, v7
	v_addc_co_u32_e32 v47, vcc, 0, v45, vcc
	global_store_dwordx2 v[46:47], v[42:43], off
	v_add_co_u32_e32 v46, vcc, s5, v44
	v_cvt_pk_bf16_f32 v42, v8, v9
	s_nop 0
	v_addc_co_u32_e32 v47, vcc, 0, v45, vcc
	v_cvt_pk_bf16_f32 v43, v10, v11
	v_add_co_u32_e32 v44, vcc, s12, v44
	global_store_dwordx2 v[46:47], v[42:43], off
	v_cvt_pk_bf16_f32 v42, v12, v13
	v_cvt_pk_bf16_f32 v43, v14, v15
	v_addc_co_u32_e32 v45, vcc, 0, v45, vcc
	global_store_dwordx2 v[44:45], v[42:43], off
	s_waitcnt lgkmcnt(0)
	s_barrier
	v_add_u32_e32 v51, v69, v97
	v_pk_mul_f32 v[0:1], v[26:27], v[0:1]
	v_pk_mul_f32 v[4:5], v[26:27], v[4:5]
	v_pk_mul_f32 v[8:9], v[26:27], v[8:9]
	s_waitcnt vmcnt(4)
	v_mov_b32_e32 v42, v224
	v_mov_b32_e32 v43, v225
	v_mov_b32_e32 v44, v226
	v_mov_b32_e32 v45, v227
	v_lshlrev_b32_e32 v46, 16, v42
	v_and_b32_e32 v47, 0xffff0000, v42
	v_lshlrev_b32_e32 v42, 16, v43
	v_and_b32_e32 v43, 0xffff0000, v43
	v_pk_mul_f32 v[42:43], v[18:19], v[42:43]
	v_pk_mul_f32 v[46:47], v[18:19], v[46:47]
	v_cvt_pk_bf16_f32 v48, v42, v43
	v_lshlrev_b32_e32 v42, 16, v44
	v_and_b32_e32 v43, 0xffff0000, v44
	v_pk_mul_f32 v[42:43], v[18:19], v[42:43]
	v_cvt_pk_bf16_f32 v17, v46, v47
	v_cvt_pk_bf16_f32 v49, v42, v43
	v_lshlrev_b32_e32 v42, 16, v45
	v_and_b32_e32 v43, 0xffff0000, v45
	v_pk_mul_f32 v[42:43], v[18:19], v[42:43]
	s_nop 0
	v_cvt_pk_bf16_f32 v50, v42, v43
	v_mov_b32_e32 v42, v228
	v_mov_b32_e32 v43, v229
	v_mov_b32_e32 v44, v230
	v_mov_b32_e32 v45, v231
	v_lshlrev_b32_e32 v46, 16, v42
	v_and_b32_e32 v47, 0xffff0000, v42
	v_lshlrev_b32_e32 v42, 16, v43
	v_and_b32_e32 v43, 0xffff0000, v43
	v_pk_mul_f32 v[46:47], v[20:21], v[46:47]
	v_pk_mul_f32 v[42:43], v[20:21], v[42:43]
	v_cvt_pk_bf16_f32 v46, v46, v47
	v_cvt_pk_bf16_f32 v47, v42, v43
	v_lshlrev_b32_e32 v42, 16, v44
	v_and_b32_e32 v43, 0xffff0000, v44
	v_pk_mul_f32 v[42:43], v[20:21], v[42:43]
	s_nop 0
	v_cvt_pk_bf16_f32 v44, v42, v43
	v_lshlrev_b32_e32 v42, 16, v45
	v_and_b32_e32 v43, 0xffff0000, v45
	v_pk_mul_f32 v[42:43], v[20:21], v[42:43]
	s_nop 0
	v_cvt_pk_bf16_f32 v42, v42, v43
	v_and_b32_e32 v43, 0xffff, v17
	v_lshrrev_b32_e32 v17, 16, v17
	v_lshl_or_b32 v43, v46, 16, v43
	v_and_or_b32 v17, v46, s59, v17
	ds_write2_b32 v51, v43, v17 offset1:68
	v_and_b32_e32 v17, 0xffff, v48
	v_lshrrev_b32_e32 v43, 16, v48
	v_lshl_or_b32 v17, v47, 16, v17
	v_and_or_b32 v43, v47, s59, v43
	ds_write2_b32 v51, v17, v43 offset0:136 offset1:204
	v_and_b32_e32 v17, 0xffff, v49
	v_lshrrev_b32_e32 v43, 16, v49
	v_lshl_or_b32 v17, v44, 16, v17
	v_and_or_b32 v43, v44, s59, v43
	v_add_u32_e32 v44, 0x400, v51
	ds_write2_b32 v44, v17, v43 offset0:16 offset1:84
	v_and_b32_e32 v17, 0xffff, v50
	v_lshrrev_b32_e32 v43, 16, v50
	v_lshl_or_b32 v17, v42, 16, v17
	v_and_or_b32 v42, v42, s59, v43
	ds_write2_b32 v44, v17, v42 offset0:152 offset1:220
	v_mov_b32_e32 v42, v232
	v_mov_b32_e32 v43, v233
	v_mov_b32_e32 v44, v234
	v_mov_b32_e32 v45, v235
	v_lshlrev_b32_e32 v46, 16, v42
	v_and_b32_e32 v47, 0xffff0000, v42
	v_lshlrev_b32_e32 v42, 16, v43
	v_and_b32_e32 v43, 0xffff0000, v43
	v_pk_mul_f32 v[42:43], v[22:23], v[42:43]
	v_pk_mul_f32 v[46:47], v[22:23], v[46:47]
	v_cvt_pk_bf16_f32 v48, v42, v43
	v_lshlrev_b32_e32 v42, 16, v44
	v_and_b32_e32 v43, 0xffff0000, v44
	v_pk_mul_f32 v[42:43], v[22:23], v[42:43]
	v_cvt_pk_bf16_f32 v17, v46, v47
	v_cvt_pk_bf16_f32 v49, v42, v43
	v_lshlrev_b32_e32 v42, 16, v45
	v_and_b32_e32 v43, 0xffff0000, v45
	v_pk_mul_f32 v[42:43], v[22:23], v[42:43]
	s_nop 0
	v_cvt_pk_bf16_f32 v50, v42, v43
	v_mov_b32_e32 v42, v236
	v_mov_b32_e32 v43, v237
	v_mov_b32_e32 v44, v238
	v_mov_b32_e32 v45, v239
	v_lshlrev_b32_e32 v46, 16, v42
	v_and_b32_e32 v47, 0xffff0000, v42
	v_lshlrev_b32_e32 v42, 16, v43
	v_and_b32_e32 v43, 0xffff0000, v43
	v_pk_mul_f32 v[46:47], v[24:25], v[46:47]
	v_pk_mul_f32 v[42:43], v[24:25], v[42:43]
	v_cvt_pk_bf16_f32 v46, v46, v47
	v_cvt_pk_bf16_f32 v47, v42, v43
	v_lshlrev_b32_e32 v42, 16, v44
	v_and_b32_e32 v43, 0xffff0000, v44
	v_pk_mul_f32 v[42:43], v[24:25], v[42:43]
	s_nop 0
	v_cvt_pk_bf16_f32 v44, v42, v43
	v_lshlrev_b32_e32 v42, 16, v45
	v_and_b32_e32 v43, 0xffff0000, v45
	v_pk_mul_f32 v[42:43], v[24:25], v[42:43]
	v_add_u32_e32 v45, v99, v101
	v_cvt_pk_bf16_f32 v42, v42, v43
	v_and_b32_e32 v43, 0xffff, v17
	v_lshrrev_b32_e32 v17, 16, v17
	v_lshl_or_b32 v43, v46, 16, v43
	v_and_or_b32 v17, v46, s59, v17
	ds_write2_b32 v45, v43, v17 offset1:68
	v_and_b32_e32 v17, 0xffff, v48
	v_lshrrev_b32_e32 v43, 16, v48
	v_lshl_or_b32 v17, v47, 16, v17
	v_and_or_b32 v43, v47, s59, v43
	ds_write2_b32 v45, v17, v43 offset0:136 offset1:204
	v_and_b32_e32 v17, 0xffff, v49
	v_lshrrev_b32_e32 v43, 16, v49
	v_lshl_or_b32 v17, v44, 16, v17
	v_and_or_b32 v43, v44, s59, v43
	v_add_u32_e32 v44, 0x400, v45
	ds_write2_b32 v44, v17, v43 offset0:16 offset1:84
	v_and_b32_e32 v17, 0xffff, v50
	v_lshrrev_b32_e32 v43, 16, v50
	v_lshl_or_b32 v17, v42, 16, v17
	v_and_or_b32 v42, v42, s59, v43
	ds_write2_b32 v44, v17, v42 offset0:152 offset1:220
	s_add_u32 s54, s54, 0x140000
	s_addc_u32 s55, s55, 0
	s_add_i32 s52, s52, 4
	s_cmp_lg_u32 s54, 0x1400000
	v_mov_b32_e32 v42, v240
	v_mov_b32_e32 v43, v241
	v_mov_b32_e32 v44, v242
	v_mov_b32_e32 v45, v243
	v_mov_b32_e32 v46, v244
	v_mov_b32_e32 v47, v245
	v_mov_b32_e32 v48, v246
	v_mov_b32_e32 v49, v247
	s_cbranch_scc0 .Lscan_nopf
	v_lshl_add_u64 v[248:249], v[40:41], 0, s[54:55]
	global_load_dwordx4 v[224:227], v[248:249], off
	v_lshl_add_u64 v[248:249], v[38:39], 0, s[54:55]
	global_load_dwordx4 v[228:231], v[248:249], off
	v_lshl_add_u64 v[248:249], v[36:37], 0, s[54:55]
	global_load_dwordx4 v[232:235], v[248:249], off
	v_lshl_add_u64 v[248:249], v[34:35], 0, s[54:55]
	global_load_dwordx4 v[236:239], v[248:249], off
	v_lshl_add_u64 v[248:249], v[32:33], 0, s[54:55]
	global_load_dwordx4 v[240:243], v[248:249], off
	v_lshl_add_u64 v[248:249], v[30:31], 0, s[54:55]
	global_load_dwordx4 v[244:247], v[248:249], off
.Lscan_nopf:
	v_and_b32_e32 v17, 0xffff, v42
	v_lshrrev_b32_e32 v42, 16, v42
	v_lshl_or_b32 v17, v46, 16, v17
	v_and_or_b32 v42, v46, s59, v42
	v_add_u32_e32 v46, 0x8800, v51
	ds_write2_b32 v46, v17, v42 offset1:68
	v_and_b32_e32 v17, 0xffff, v43
	v_lshrrev_b32_e32 v42, 16, v43
	v_lshl_or_b32 v17, v47, 16, v17
	v_and_or_b32 v42, v47, s59, v42
	ds_write2_b32 v46, v17, v42 offset0:136 offset1:204
	v_and_b32_e32 v17, 0xffff, v44
	v_lshrrev_b32_e32 v42, 16, v44
	v_lshl_or_b32 v17, v48, 16, v17
	v_and_or_b32 v42, v48, s59, v42
	v_add_u32_e32 v43, 0x8c00, v51
	ds_write2_b32 v43, v17, v42 offset0:16 offset1:84
	v_and_b32_e32 v17, 0xffff, v45
	v_lshrrev_b32_e32 v42, 16, v45
	v_lshl_or_b32 v17, v49, 16, v17
	v_and_or_b32 v42, v49, s59, v42
	ds_write2_b32 v43, v17, v42 offset0:152 offset1:220
	s_waitcnt lgkmcnt(0)
	s_barrier
	ds_read_b128 v[48:51], v174
	v_mov_b32_e32 v17, v16
	v_pk_mul_f32 v[2:3], v[16:17], v[2:3]
	v_pk_mul_f32 v[6:7], v[16:17], v[6:7]
	v_pk_mul_f32 v[10:11], v[16:17], v[10:11]
	v_pk_mul_f32 v[46:47], v[16:17], v[14:15]
	v_add_u32_e32 v17, v103, v105
	v_pk_mul_f32 v[44:45], v[26:27], v[12:13]
	ds_read_b128 v[12:15], v17 offset:34816
	s_waitcnt lgkmcnt(0)
	v_mfma_f32_16x16x32_bf16 v[12:15], v[48:51], v[12:15], v[0:3]
	s_nop 2
	ds_read_b128 v[0:3], v17 offset:39168
	v_add_u32_e32 v42, v103, v107
	s_waitcnt lgkmcnt(0)
	v_mfma_f32_16x16x32_bf16 v[4:7], v[48:51], v[0:3], v[4:7]
	ds_read_b128 v[0:3], v17 offset:43520
	s_waitcnt lgkmcnt(0)
	v_mfma_f32_16x16x32_bf16 v[0:3], v[48:51], v[0:3], v[8:11]
	s_nop 2
	ds_read_b128 v[8:11], v42 offset:34816
	s_waitcnt lgkmcnt(0)
	v_mfma_f32_16x16x32_bf16 v[8:11], v[48:51], v[8:11], v[44:47]
	s_nop 2
	ds_read_b128 v[44:47], v174 offset:64
	ds_read_b128 v[48:51], v17 offset:34880
	s_waitcnt lgkmcnt(0)
	v_mfma_f32_16x16x32_bf16 v[12:15], v[44:47], v[48:51], v[12:15]
	ds_read_b128 v[48:51], v17 offset:39232
	s_waitcnt lgkmcnt(0)
	v_mfma_f32_16x16x32_bf16 v[4:7], v[44:47], v[48:51], v[4:7]
	ds_read_b128 v[48:51], v17 offset:43584
	s_waitcnt lgkmcnt(0)
	v_mfma_f32_16x16x32_bf16 v[0:3], v[44:47], v[48:51], v[0:3]
	ds_read_b128 v[48:51], v42 offset:34880
	s_waitcnt lgkmcnt(0)
	v_mfma_f32_16x16x32_bf16 v[8:11], v[44:47], v[48:51], v[8:11]
	ds_read_b128 v[44:47], v174 offset:128
	ds_read_b128 v[48:51], v17 offset:34944
	s_waitcnt lgkmcnt(0)
	v_mfma_f32_16x16x32_bf16 v[12:15], v[44:47], v[48:51], v[12:15]
	ds_read_b128 v[48:51], v17 offset:39296
	s_waitcnt lgkmcnt(0)
	v_mfma_f32_16x16x32_bf16 v[4:7], v[44:47], v[48:51], v[4:7]
	ds_read_b128 v[48:51], v17 offset:43648
	s_waitcnt lgkmcnt(0)
	v_mfma_f32_16x16x32_bf16 v[48:51], v[44:47], v[48:51], v[0:3]
	s_nop 2
	ds_read_b128 v[0:3], v42 offset:34944
	s_waitcnt lgkmcnt(0)
	v_mfma_f32_16x16x32_bf16 v[44:47], v[44:47], v[0:3], v[8:11]
	ds_read_b128 v[52:55], v174 offset:192
	ds_read_b128 v[0:3], v17 offset:35008
	s_nop 0
	ds_read_b128 v[8:11], v17 offset:39360
	s_waitcnt lgkmcnt(1)
	v_mfma_f32_16x16x32_bf16 v[0:3], v[52:55], v[0:3], v[12:15]
	s_nop 2
	ds_read_b128 v[12:15], v42 offset:35008
	s_waitcnt lgkmcnt(1)
	v_mfma_f32_16x16x32_bf16 v[4:7], v[52:55], v[8:11], v[4:7]
	ds_read_b128 v[8:11], v17 offset:43712
	s_waitcnt lgkmcnt(0)
	v_mfma_f32_16x16x32_bf16 v[8:11], v[52:55], v[8:11], v[48:51]
	v_mfma_f32_16x16x32_bf16 v[12:15], v[52:55], v[12:15], v[44:47]
	s_cbranch_scc1 .LBB0_309
	s_lshl_b32 s4, s65, 2
	s_or_b32 s52, s4, s0
	s_ashr_i32 s53, s52, 31
	s_lshl_b64 s[52:53], s[52:53], 17
	s_add_u32 s10, s10, s52
	v_lshlrev_b32_e32 v16, 2, v68
	s_addc_u32 s11, s11, s53
	v_lshl_or_b32 v152, s64, 8, v16
	v_lshl_add_u64 v[16:17], s[10:11], 0, v[152:153]
	s_mov_b64 s[10:11], 0x6400000
	v_lshl_add_u64 v[16:17], v[16:17], 0, s[10:11]
	v_lshl_add_u64 v[18:19], v[16:17], 0, v[112:113]
	v_lshl_add_u64 v[20:21], v[16:17], 0, v[114:115]
	v_readlane_b32 s92, v254, 25
	v_readlane_b32 s84, v254, 51
	flat_store_dword v[18:19], v0
	flat_store_dword v[20:21], v1
	v_lshl_add_u64 v[0:1], v[16:17], 0, v[116:117]
	v_lshl_add_u64 v[16:17], v[16:17], 0, v[118:119]
	v_readlane_b32 s93, v254, 26
	v_readlane_b32 s94, v254, 27
	v_readlane_b32 s95, v254, 28
	v_readlane_b32 s85, v254, 52
	flat_store_dword v[0:1], v2
	flat_store_dword v[16:17], v3
	flat_store_dword v[18:19], v4 offset:64
	flat_store_dword v[20:21], v5 offset:64
	flat_store_dword v[0:1], v6 offset:64
	flat_store_dword v[16:17], v7 offset:64
	flat_store_dword v[18:19], v8 offset:128
	flat_store_dword v[20:21], v9 offset:128
	flat_store_dword v[0:1], v10 offset:128
	flat_store_dword v[16:17], v11 offset:128
	flat_store_dword v[18:19], v12 offset:192
	flat_store_dword v[20:21], v13 offset:192
	flat_store_dword v[0:1], v14 offset:192
	flat_store_dword v[16:17], v15 offset:192
	s_branch .LBB0_281

.LBB0_315:
	s_or_b64 exec, exec, s[10:11]
	s_lshl_b32 s71, s87, 8
	s_mul_i32 s0, s52, 0x2800
	s_add_u32 s0, s54, s0
	s_addc_u32 s4, s55, 0
	s_lshl_b32 s5, s87, 9
	s_add_u32 s0, s0, s5
	s_addc_u32 s4, s4, 0
	s_add_u32 s10, s0, 0x1800
	s_addc_u32 s11, s4, 0
	s_mulk_i32 s86, 0x2800
	s_add_u32 s0, s54, s86
	s_addc_u32 s4, s55, 0
	s_add_u32 s0, s0, s5
	s_addc_u32 s4, s4, 0
	s_add_u32 s64, s0, 0xa004000
	s_addc_u32 s65, s4, 0
	s_add_u32 s86, s0, 0xa006800
	s_addc_u32 s87, s4, 0
	s_add_u32 s88, s0, 0xa009000
	s_addc_u32 s89, s4, 0
	s_add_u32 s96, s0, 0xa00b800
	s_addc_u32 s97, s4, 0
	s_add_u32 vcc_lo, s0, 0xa00e000
	s_addc_u32 vcc_hi, s4, 0
	s_or_b32 s0, s85, 0x4006
	s_mulk_i32 s0, 0x2800
	s_add_u32 s0, s54, s0
	s_addc_u32 s4, s55, 0
	s_add_u32 s0, s0, s5
	s_addc_u32 s4, s4, 0
	s_add_u32 s12, s0, 0x1800
	s_addc_u32 s13, s4, 0
	s_or_b32 s0, s85, 0x4007
	s_mulk_i32 s0, 0x2800
	s_add_u32 s0, s54, s0
	s_addc_u32 s4, s55, 0
	s_add_u32 s0, s0, s5
	s_addc_u32 s5, s4, 0
	v_and_b32_e32 v32, 0xff, v175
	s_add_u32 s4, s0, 0x1800
	v_lshlrev_b32_e32 v16, 2, v175
	v_lshlrev_b32_e32 v152, 1, v32
	s_addc_u32 s5, s5, 0
	v_and_b32_e32 v35, 0xfc, v16
	v_lshl_add_u64 v[0:1], s[10:11], 0, v[152:153]
	v_lshl_add_u64 v[2:3], s[64:65], 0, v[152:153]
	v_lshl_add_u64 v[4:5], s[86:87], 0, v[152:153]
	v_lshl_add_u64 v[6:7], s[88:89], 0, v[152:153]
	v_lshl_add_u64 v[8:9], s[96:97], 0, v[152:153]
	v_lshl_add_u64 v[10:11], vcc, 0, v[152:153]
	v_lshl_add_u64 v[12:13], s[12:13], 0, v[152:153]
	v_lshl_add_u64 v[14:15], s[4:5], 0, v[152:153]
	v_lshlrev_b32_e32 v152, 1, v35
	v_lshl_add_u64 v[16:17], s[10:11], 0, v[152:153]
	v_lshl_add_u64 v[18:19], s[64:65], 0, v[152:153]
	v_lshl_add_u64 v[20:21], s[86:87], 0, v[152:153]
	v_lshl_add_u64 v[22:23], s[88:89], 0, v[152:153]
	v_lshl_add_u64 v[24:25], s[96:97], 0, v[152:153]
	v_lshl_add_u64 v[26:27], vcc, 0, v[152:153]
	v_lshl_add_u64 v[28:29], s[12:13], 0, v[152:153]
	v_lshl_add_u64 v[30:31], s[4:5], 0, v[152:153]
	global_load_dwordx2 v[16:17], v[16:17], off
	v_ashrrev_i32_e32 v195, 6, v175
	global_load_dwordx2 v[18:19], v[18:19], off
	v_readlane_b32 s72, v254, 25
	global_load_dwordx2 v[20:21], v[20:21], off
	v_lshlrev_b32_e32 v36, 4, v195
	global_load_dwordx2 v[22:23], v[22:23], off
	v_readlane_b32 s73, v254, 26
	global_load_dwordx2 v[24:25], v[24:25], off
	v_readlane_b32 s74, v254, 27
	global_load_dwordx2 v[26:27], v[26:27], off
	v_readlane_b32 s75, v254, 28
	global_load_dwordx2 v[28:29], v[28:29], off
	v_ashrrev_i32_e32 v37, 31, v36
	global_load_dwordx2 v[30:31], v[30:31], off
	s_nop 0
	global_load_ushort v194, v[0:1], off
	global_load_ushort v193, v[2:3], off
	global_load_ushort v181, v[4:5], off
	global_load_ushort v180, v[6:7], off
	global_load_ushort v179, v[8:9], off
	global_load_ushort v178, v[10:11], off
	global_load_ushort v177, v[12:13], off
	global_load_ushort v176, v[14:15], off
	s_lshl_b32 s0, s53, 7
	s_mov_b64 s[94:95], s[76:77]
	s_mov_b64 s[92:93], s[78:79]
	s_mov_b64 s[4:5], s[72:73]
	v_lshl_add_u64 v[0:1], v[36:37], 0, s[0:1]
	v_readlane_b32 s72, v253, 42
	v_mul_f32_e32 v34, 0x41000000, v33
	v_lshlrev_b64 v[0:1], 10, v[0:1]
	v_readlane_b32 s76, v253, 46
	v_readlane_b32 s77, v253, 47
	v_exp_f32_e32 v34, v34
	v_lshlrev_b32_e32 v152, 2, v35
	v_lshl_add_u64 v[2:3], s[76:77], 0, v[0:1]
	v_lshl_add_u64 v[136:137], v[2:3], 0, v[152:153]
	v_mov_b32_e32 v249, 0
	global_load_dwordx4 v[222:225], v[136:137], off nt
	global_load_dwordx4 v[238:241], v[136:137], off nt
	global_load_dwordx4 v[226:229], v[136:137], off offset:1024 nt
	global_load_dwordx4 v[238:241], v[136:137], off offset:1024 nt
	global_load_dwordx4 v[230:233], v[136:137], off offset:2048 nt
	global_load_dwordx4 v[238:241], v[136:137], off offset:2048 nt
	global_load_dwordx4 v[234:237], v[136:137], off offset:3072 nt
	global_load_dwordx4 v[238:241], v[136:137], off offset:3072 nt
	v_and_b32_e32 v2, 63, v175
	v_lshl_or_b32 v0, v2, 4, v0
	v_mov_b32_e32 v138, v34
	v_lshl_add_u64 v[140:141], s[4:5], 0, v[0:1]
	v_mov_b32_e32 v0, 0
	v_mov_b32_e32 v139, v34
	v_lshl_add_u32 v196, v195, 9, 0
	s_mov_b64 s[10:11], 0
	v_mov_b32_e32 v1, v0
	v_mov_b32_e32 v2, v0
	v_mov_b32_e32 v3, v0
	v_mov_b32_e32 v4, v0
	v_mov_b32_e32 v5, v0
	v_mov_b32_e32 v6, v0
	v_mov_b32_e32 v7, v0
	v_mov_b32_e32 v8, v0
	v_mov_b32_e32 v9, v0
	v_mov_b32_e32 v10, v0
	v_mov_b32_e32 v11, v0
	v_mov_b32_e32 v12, v0
	v_mov_b32_e32 v13, v0
	v_mov_b32_e32 v14, v0
	v_mov_b32_e32 v15, v0
	v_readlane_b32 s73, v253, 43
	v_readlane_b32 s74, v253, 44
	v_readlane_b32 s75, v253, 45
	v_readlane_b32 s78, v253, 48
	v_readlane_b32 s79, v253, 49
	v_readlane_b32 s80, v253, 50
	v_readlane_b32 s81, v253, 51
	v_readlane_b32 s82, v253, 52
	v_readlane_b32 s83, v253, 53
	v_readlane_b32 s84, v253, 54
	v_readlane_b32 s85, v253, 55
	v_readlane_b32 s86, v253, 56
	v_readlane_b32 s87, v253, 57
	s_waitcnt vmcnt(8) lgkmcnt(0)
	v_lshlrev_b32_e32 v36, 16, v16
	v_and_b32_e32 v37, 0xffff0000, v16
	v_lshlrev_b32_e32 v38, 16, v17
	v_and_b32_e32 v39, 0xffff0000, v17
	v_lshlrev_b32_e32 v40, 16, v18
	v_and_b32_e32 v41, 0xffff0000, v18
	v_lshlrev_b32_e32 v42, 16, v19
	v_and_b32_e32 v43, 0xffff0000, v19
	v_lshlrev_b32_e32 v44, 16, v20
	v_and_b32_e32 v45, 0xffff0000, v20
	v_lshlrev_b32_e32 v46, 16, v21
	v_and_b32_e32 v47, 0xffff0000, v21
	v_lshlrev_b32_e32 v48, 16, v22
	v_and_b32_e32 v49, 0xffff0000, v22
	v_lshlrev_b32_e32 v50, 16, v23
	v_and_b32_e32 v51, 0xffff0000, v23
	v_lshlrev_b32_e32 v52, 16, v24
	v_and_b32_e32 v53, 0xffff0000, v24
	v_lshlrev_b32_e32 v54, 16, v25
	v_and_b32_e32 v55, 0xffff0000, v25
	v_lshlrev_b32_e32 v56, 16, v26
	v_and_b32_e32 v57, 0xffff0000, v26
	v_lshlrev_b32_e32 v58, 16, v27
	v_and_b32_e32 v59, 0xffff0000, v27
	v_lshlrev_b32_e32 v60, 16, v28
	v_and_b32_e32 v61, 0xffff0000, v28
	v_lshlrev_b32_e32 v62, 16, v29
	v_and_b32_e32 v63, 0xffff0000, v29
	v_lshlrev_b32_e32 v132, 16, v30
	v_and_b32_e32 v133, 0xffff0000, v30
	v_lshlrev_b32_e32 v134, 16, v31
	v_and_b32_e32 v135, 0xffff0000, v31
	v_mov_b32_e32 v24, v0
	v_mov_b32_e32 v25, v0
	v_mov_b32_e32 v26, v0
	v_mov_b32_e32 v27, v0
	v_mov_b32_e32 v28, v0
	v_mov_b32_e32 v29, v0
	v_mov_b32_e32 v30, v0
	v_mov_b32_e32 v31, v0
	v_mov_b32_e32 v16, v0
	v_mov_b32_e32 v17, v0
	v_mov_b32_e32 v18, v0
	v_mov_b32_e32 v19, v0
	v_mov_b32_e32 v20, v0
	v_mov_b32_e32 v21, v0
	v_mov_b32_e32 v22, v0
	v_mov_b32_e32 v23, v0
.LBB0_316:
	v_mov_b32_e32 v248, 0x1000
	s_cmpk_eq_i32 s10, 0x3000
	s_cbranch_scc0 .Lrs_notlast
	v_mov_b32_e32 v248, 0
.Lrs_notlast:
	v_lshl_add_u64 v[142:143], v[136:137], 0, s[10:11]
	v_lshl_add_u64 v[250:251], v[142:143], 0, v[248:249]
	s_waitcnt vmcnt(7)
	s_nop 1
	v_mov_b32_e32 v198, v222
	v_mov_b32_e32 v199, v223
	v_mov_b32_e32 v200, v224
	v_mov_b32_e32 v201, v225
	global_load_dwordx4 v[222:225], v[250:251], off nt
	ds_read_b128 v[202:205], v196
	ds_read_b128 v[206:209], v196 offset:16
	ds_read_b128 v[210:213], v196 offset:4096
	ds_read_b128 v[214:217], v196 offset:4112
	v_mov_b32_e32 v35, v34
	s_mov_b32 s0, 0x6800000
	s_waitcnt lgkmcnt(0)
	v_pk_fma_f32 v[148:149], v[200:201], v[202:203], v[26:27] op_sel_hi:[1,0,1]
	s_waitcnt lgkmcnt(2)
	v_pk_fma_f32 v[26:27], v[198:199], v[206:207], v[28:29] op_sel_hi:[1,0,1]
	v_pk_fma_f32 v[28:29], v[200:201], v[206:207], v[30:31] op_sel_hi:[1,0,1]
	s_waitcnt lgkmcnt(0)
	v_pk_mul_f32 v[30:31], v[214:215], v[54:55] op_sel_hi:[0,1]
	v_pk_fma_f32 v[146:147], v[198:199], v[202:203], v[24:25] op_sel_hi:[1,0,1]
	v_pk_mul_f32 v[24:25], v[214:215], v[52:53] op_sel_hi:[0,1]
	v_pk_fma_f32 v[30:31], v[210:211], v[38:39], v[30:31] op_sel_hi:[0,1,1]
	v_pk_fma_f32 v[24:25], v[210:211], v[36:37], v[24:25] op_sel_hi:[0,1,1]
	v_pk_fma_f32 v[144:145], v[34:35], v[200:201], v[30:31]
	v_pk_fma_f32 v[30:31], v[198:199], v[202:203], v[4:5] op_sel:[0,1,0]
	v_pk_mul_f32 v[4:5], v[214:215], v[56:57] op_sel:[1,0]
	v_pk_fma_f32 v[24:25], v[138:139], v[198:199], v[24:25]
	v_pk_fma_f32 v[158:159], v[200:201], v[202:203], v[6:7] op_sel:[0,1,0]
	v_pk_mul_f32 v[6:7], v[214:215], v[58:59] op_sel:[1,0]
	v_pk_fma_f32 v[4:5], v[210:211], v[40:41], v[4:5] op_sel:[1,0,0]
	v_pk_fma_f32 v[150:151], v[198:199], v[206:207], v[16:17] op_sel:[0,1,0]
	v_pk_fma_f32 v[6:7], v[210:211], v[42:43], v[6:7] op_sel:[1,0,0]
	v_pk_add_f32 v[4:5], v[4:5], v[24:25]
	v_pk_fma_f32 v[16:17], v[198:199], v[204:205], v[8:9] op_sel_hi:[1,0,1]
	v_pk_fma_f32 v[24:25], v[200:201], v[204:205], v[10:11] op_sel_hi:[1,0,1]
	v_pk_mul_f32 v[8:9], v[216:217], v[62:63] op_sel_hi:[0,1]
	v_pk_mul_f32 v[10:11], v[216:217], v[60:61] op_sel_hi:[0,1]
	v_pk_add_f32 v[6:7], v[6:7], v[144:145]
	v_pk_fma_f32 v[8:9], v[212:213], v[46:47], v[8:9] op_sel_hi:[0,1,1]
	v_pk_fma_f32 v[10:11], v[212:213], v[44:45], v[10:11] op_sel_hi:[0,1,1]
	v_pk_fma_f32 v[160:161], v[200:201], v[206:207], v[18:19] op_sel:[0,1,0]
	v_pk_fma_f32 v[18:19], v[198:199], v[208:209], v[20:21] op_sel_hi:[1,0,1]
	v_pk_fma_f32 v[20:21], v[200:201], v[208:209], v[22:23] op_sel_hi:[1,0,1]
	v_pk_add_f32 v[22:23], v[10:11], v[4:5]
	v_pk_add_f32 v[144:145], v[8:9], v[6:7]
	v_mov_b32_e32 v6, v205
	v_mov_b32_e32 v10, v209
	v_pk_fma_f32 v[4:5], v[198:199], v[6:7], v[12:13] op_sel_hi:[1,0,1]
	v_pk_fma_f32 v[8:9], v[200:201], v[6:7], v[14:15] op_sel_hi:[1,0,1]
	v_pk_fma_f32 v[6:7], v[198:199], v[10:11], v[0:1] op_sel_hi:[1,0,1]
	v_mov_b32_e32 v0, v217
	v_pk_fma_f32 v[10:11], v[200:201], v[10:11], v[2:3] op_sel_hi:[1,0,1]
	v_pk_mul_f32 v[2:3], v[0:1], v[134:135] op_sel_hi:[0,1]
	v_pk_mul_f32 v[0:1], v[0:1], v[132:133] op_sel_hi:[0,1]
	v_mov_b32_e32 v12, v213
	v_pk_fma_f32 v[0:1], v[12:13], v[48:49], v[0:1] op_sel_hi:[0,1,1]
	v_pk_fma_f32 v[2:3], v[12:13], v[50:51], v[2:3] op_sel_hi:[0,1,1]
	v_lshl_add_u64 v[12:13], v[140:141], 0, s[10:11]
	v_pk_add_f32 v[2:3], v[2:3], v[144:145]
	v_add_co_u32_e32 v144, vcc, s0, v12
	v_pk_add_f32 v[0:1], v[0:1], v[22:23]
	s_nop 0
	v_addc_co_u32_e32 v145, vcc, 0, v13, vcc
	global_store_dwordx4 v[144:145], v[0:3], off nt
	s_waitcnt vmcnt(7)
	s_nop 1
	v_mov_b32_e32 v198, v226
	v_mov_b32_e32 v199, v227
	v_mov_b32_e32 v200, v228
	v_mov_b32_e32 v201, v229
	global_load_dwordx4 v[226:229], v[250:251], off offset:1024 nt
	ds_read_b128 v[202:205], v196 offset:32
	ds_read_b128 v[206:209], v196 offset:48
	ds_read_b128 v[210:213], v196 offset:4128
	ds_read_b128 v[214:217], v196 offset:4144
	s_add_u32 s10, s10, 0x1000
	s_addc_u32 s11, s11, 0
	s_cmpk_eq_i32 s10, 0x4000
	s_waitcnt lgkmcnt(0)
	v_pk_mul_f32 v[22:23], v[214:215], v[52:53] op_sel_hi:[0,1]
	v_pk_fma_f32 v[22:23], v[210:211], v[36:37], v[22:23] op_sel_hi:[0,1,1]
	v_pk_fma_f32 v[14:15], v[198:199], v[206:207], v[26:27] op_sel_hi:[1,0,1]
	v_pk_mul_f32 v[26:27], v[214:215], v[54:55] op_sel_hi:[0,1]
	v_pk_fma_f32 v[0:1], v[200:201], v[202:203], v[148:149] op_sel_hi:[1,0,1]
	v_pk_fma_f32 v[12:13], v[200:201], v[206:207], v[28:29] op_sel_hi:[1,0,1]
	v_pk_fma_f32 v[26:27], v[210:211], v[38:39], v[26:27] op_sel_hi:[0,1,1]
	v_pk_fma_f32 v[28:29], v[200:201], v[202:203], v[158:159] op_sel:[0,1,0]
	v_pk_fma_f32 v[148:149], v[198:199], v[206:207], v[150:151] op_sel:[0,1,0]
	v_pk_mul_f32 v[150:151], v[214:215], v[56:57] op_sel:[1,0]
	v_pk_mul_f32 v[158:159], v[214:215], v[58:59] op_sel:[1,0]
	v_pk_fma_f32 v[2:3], v[198:199], v[202:203], v[146:147] op_sel_hi:[1,0,1]
	v_pk_fma_f32 v[26:27], v[34:35], v[200:201], v[26:27]
	v_pk_fma_f32 v[22:23], v[138:139], v[198:199], v[22:23]
	v_pk_fma_f32 v[146:147], v[200:201], v[206:207], v[160:161] op_sel:[0,1,0]
	v_pk_fma_f32 v[158:159], v[210:211], v[42:43], v[158:159] op_sel:[1,0,0]
	v_pk_fma_f32 v[150:151], v[210:211], v[40:41], v[150:151] op_sel:[1,0,0]
	v_pk_fma_f32 v[160:161], v[200:201], v[208:209], v[20:21] op_sel_hi:[1,0,1]
	v_mov_b32_e32 v20, v205
	v_pk_add_f32 v[26:27], v[158:159], v[26:27]
	v_pk_add_f32 v[22:23], v[150:151], v[22:23]
	v_pk_fma_f32 v[150:151], v[200:201], v[204:205], v[24:25] op_sel_hi:[1,0,1]
	v_pk_fma_f32 v[158:159], v[198:199], v[204:205], v[16:17] op_sel_hi:[1,0,1]
	v_pk_fma_f32 v[204:205], v[198:199], v[20:21], v[4:5] op_sel_hi:[1,0,1]
	v_mov_b32_e32 v4, v209
	v_pk_fma_f32 v[30:31], v[198:199], v[202:203], v[30:31] op_sel:[0,1,0]
	v_pk_fma_f32 v[184:185], v[198:199], v[208:209], v[18:19] op_sel_hi:[1,0,1]
	v_pk_mul_f32 v[16:17], v[216:217], v[62:63] op_sel_hi:[0,1]
	v_pk_mul_f32 v[18:19], v[216:217], v[60:61] op_sel_hi:[0,1]
	v_pk_fma_f32 v[202:203], v[200:201], v[20:21], v[8:9] op_sel_hi:[1,0,1]
	v_pk_fma_f32 v[200:201], v[200:201], v[4:5], v[10:11] op_sel_hi:[1,0,1]
	v_pk_fma_f32 v[198:199], v[198:199], v[4:5], v[6:7] op_sel_hi:[1,0,1]
	v_mov_b32_e32 v4, v217
	v_pk_fma_f32 v[16:17], v[212:213], v[46:47], v[16:17] op_sel_hi:[0,1,1]
	v_pk_fma_f32 v[18:19], v[212:213], v[44:45], v[18:19] op_sel_hi:[0,1,1]
	v_pk_mul_f32 v[6:7], v[4:5], v[134:135] op_sel_hi:[0,1]
	v_pk_mul_f32 v[4:5], v[4:5], v[132:133] op_sel_hi:[0,1]
	v_mov_b32_e32 v8, v213
	v_pk_add_f32 v[18:19], v[18:19], v[22:23]
	v_pk_add_f32 v[16:17], v[16:17], v[26:27]
	v_pk_fma_f32 v[4:5], v[8:9], v[48:49], v[4:5] op_sel_hi:[0,1,1]
	v_pk_fma_f32 v[6:7], v[8:9], v[50:51], v[6:7] op_sel_hi:[0,1,1]
	v_pk_add_f32 v[6:7], v[6:7], v[16:17]
	v_pk_add_f32 v[4:5], v[4:5], v[18:19]
	global_store_dwordx4 v[144:145], v[4:7], off offset:1024 nt
	s_waitcnt vmcnt(7)
	s_nop 1
	v_mov_b32_e32 v4, v230
	v_mov_b32_e32 v5, v231
	v_mov_b32_e32 v6, v232
	v_mov_b32_e32 v7, v233
	global_load_dwordx4 v[230:233], v[250:251], off offset:2048 nt
	ds_read_b128 v[8:11], v196 offset:64
	ds_read_b128 v[16:19], v196 offset:80
	ds_read_b128 v[20:23], v196 offset:4160
	ds_read_b128 v[24:27], v196 offset:4176
	s_waitcnt lgkmcnt(0)
	v_pk_fma_f32 v[206:207], v[6:7], v[8:9], v[0:1] op_sel_hi:[1,0,1]
	v_pk_fma_f32 v[208:209], v[4:5], v[8:9], v[2:3] op_sel_hi:[1,0,1]
	v_pk_fma_f32 v[210:211], v[6:7], v[16:17], v[12:13] op_sel_hi:[1,0,1]
	v_pk_mul_f32 v[0:1], v[24:25], v[52:53] op_sel_hi:[0,1]
	v_pk_mul_f32 v[2:3], v[24:25], v[54:55] op_sel_hi:[0,1]
	v_pk_mul_f32 v[12:13], v[24:25], v[56:57] op_sel:[1,0]
	v_pk_mul_f32 v[24:25], v[24:25], v[58:59] op_sel:[1,0]
	v_pk_fma_f32 v[2:3], v[20:21], v[38:39], v[2:3] op_sel_hi:[0,1,1]
	v_pk_fma_f32 v[0:1], v[20:21], v[36:37], v[0:1] op_sel_hi:[0,1,1]
	v_pk_fma_f32 v[24:25], v[20:21], v[42:43], v[24:25] op_sel:[1,0,0]
	v_pk_fma_f32 v[12:13], v[20:21], v[40:41], v[12:13] op_sel:[1,0,0]
	v_pk_fma_f32 v[20:21], v[4:5], v[10:11], v[158:159] op_sel_hi:[1,0,1]
	v_pk_fma_f32 v[150:151], v[6:7], v[10:11], v[150:151] op_sel_hi:[1,0,1]
	v_mov_b32_e32 v10, v11
	v_pk_fma_f32 v[2:3], v[34:35], v[6:7], v[2:3]
	v_pk_fma_f32 v[0:1], v[138:139], v[4:5], v[0:1]
	v_pk_fma_f32 v[204:205], v[4:5], v[10:11], v[204:205] op_sel_hi:[1,0,1]
	v_pk_fma_f32 v[202:203], v[6:7], v[10:11], v[202:203] op_sel_hi:[1,0,1]
	v_mov_b32_e32 v10, v19
	v_pk_fma_f32 v[14:15], v[4:5], v[16:17], v[14:15] op_sel_hi:[1,0,1]
	v_pk_fma_f32 v[212:213], v[6:7], v[8:9], v[28:29] op_sel:[0,1,0]
	v_pk_fma_f32 v[8:9], v[4:5], v[8:9], v[30:31] op_sel:[0,1,0]
	v_pk_fma_f32 v[214:215], v[6:7], v[16:17], v[146:147] op_sel:[0,1,0]
	v_pk_fma_f32 v[16:17], v[4:5], v[16:17], v[148:149] op_sel:[0,1,0]
	v_pk_add_f32 v[2:3], v[24:25], v[2:3]
	v_pk_add_f32 v[0:1], v[12:13], v[0:1]
	v_pk_fma_f32 v[184:185], v[4:5], v[18:19], v[184:185] op_sel_hi:[1,0,1]
	v_pk_mul_f32 v[12:13], v[26:27], v[62:63] op_sel_hi:[0,1]
	v_pk_mul_f32 v[24:25], v[26:27], v[60:61] op_sel_hi:[0,1]
	v_pk_fma_f32 v[218:219], v[4:5], v[10:11], v[198:199] op_sel_hi:[1,0,1]
	v_mov_b32_e32 v4, v27
	v_pk_fma_f32 v[216:217], v[6:7], v[18:19], v[160:161] op_sel_hi:[1,0,1]
	v_pk_fma_f32 v[12:13], v[22:23], v[46:47], v[12:13] op_sel_hi:[0,1,1]
	v_pk_fma_f32 v[24:25], v[22:23], v[44:45], v[24:25] op_sel_hi:[0,1,1]
	v_pk_fma_f32 v[220:221], v[6:7], v[10:11], v[200:201] op_sel_hi:[1,0,1]
	v_pk_mul_f32 v[6:7], v[4:5], v[134:135] op_sel_hi:[0,1]
	v_pk_mul_f32 v[4:5], v[4:5], v[132:133] op_sel_hi:[0,1]
	v_mov_b32_e32 v10, v23
	v_pk_add_f32 v[0:1], v[24:25], v[0:1]
	v_pk_add_f32 v[2:3], v[12:13], v[2:3]
	v_pk_fma_f32 v[4:5], v[10:11], v[48:49], v[4:5] op_sel_hi:[0,1,1]
	v_pk_fma_f32 v[6:7], v[10:11], v[50:51], v[6:7] op_sel_hi:[0,1,1]
	v_pk_add_f32 v[2:3], v[6:7], v[2:3]
	v_pk_add_f32 v[0:1], v[4:5], v[0:1]
	global_store_dwordx4 v[144:145], v[0:3], off offset:2048 nt
	s_waitcnt vmcnt(7)
	s_nop 1
	v_mov_b32_e32 v0, v234
	v_mov_b32_e32 v1, v235
	v_mov_b32_e32 v2, v236
	v_mov_b32_e32 v3, v237
	global_load_dwordx4 v[234:237], v[250:251], off offset:3072 nt
	ds_read_b128 v[10:13], v196 offset:96
	ds_read_b128 v[146:149], v196 offset:112
	ds_read_b128 v[158:161], v196 offset:4192
	ds_read_b128 v[198:201], v196 offset:4208
	v_add_u32_e32 v196, 0x80, v196
	s_waitcnt lgkmcnt(0)
	v_pk_mul_f32 v[4:5], v[198:199], v[52:53] op_sel_hi:[0,1]
	v_pk_mul_f32 v[6:7], v[198:199], v[54:55] op_sel_hi:[0,1]
	v_pk_fma_f32 v[6:7], v[158:159], v[38:39], v[6:7] op_sel_hi:[0,1,1]
	v_pk_fma_f32 v[4:5], v[158:159], v[36:37], v[4:5] op_sel_hi:[0,1,1]
	v_pk_fma_f32 v[26:27], v[2:3], v[10:11], v[206:207] op_sel_hi:[1,0,1]
	v_pk_fma_f32 v[24:25], v[0:1], v[10:11], v[208:209] op_sel_hi:[1,0,1]
	v_pk_fma_f32 v[28:29], v[0:1], v[146:147], v[14:15] op_sel_hi:[1,0,1]
	v_pk_fma_f32 v[14:15], v[34:35], v[2:3], v[6:7]
	v_pk_fma_f32 v[22:23], v[138:139], v[0:1], v[4:5]
	v_pk_fma_f32 v[6:7], v[2:3], v[10:11], v[212:213] op_sel:[0,1,0]
	v_pk_fma_f32 v[4:5], v[0:1], v[10:11], v[8:9] op_sel:[0,1,0]
	v_pk_mul_f32 v[8:9], v[198:199], v[56:57] op_sel:[1,0]
	v_pk_mul_f32 v[10:11], v[198:199], v[58:59] op_sel:[1,0]
	v_pk_fma_f32 v[30:31], v[2:3], v[146:147], v[210:211] op_sel_hi:[1,0,1]
	v_pk_fma_f32 v[18:19], v[2:3], v[146:147], v[214:215] op_sel:[0,1,0]
	v_pk_fma_f32 v[16:17], v[0:1], v[146:147], v[16:17] op_sel:[0,1,0]
	v_pk_fma_f32 v[10:11], v[158:159], v[42:43], v[10:11] op_sel:[1,0,0]
	v_pk_fma_f32 v[8:9], v[158:159], v[40:41], v[8:9] op_sel:[1,0,0]
	v_pk_mul_f32 v[146:147], v[200:201], v[62:63] op_sel_hi:[0,1]
	v_pk_add_f32 v[14:15], v[10:11], v[14:15]
	v_pk_add_f32 v[142:143], v[8:9], v[22:23]
	v_pk_fma_f32 v[10:11], v[2:3], v[12:13], v[150:151] op_sel_hi:[1,0,1]
	v_pk_fma_f32 v[8:9], v[0:1], v[12:13], v[20:21] op_sel_hi:[1,0,1]
	v_pk_fma_f32 v[22:23], v[2:3], v[148:149], v[216:217] op_sel_hi:[1,0,1]
	v_pk_fma_f32 v[20:21], v[0:1], v[148:149], v[184:185] op_sel_hi:[1,0,1]
	v_pk_mul_f32 v[150:151], v[200:201], v[60:61] op_sel_hi:[0,1]
	v_pk_fma_f32 v[146:147], v[160:161], v[46:47], v[146:147] op_sel_hi:[0,1,1]
	v_mov_b32_e32 v12, v13
	v_mov_b32_e32 v148, v149
	v_pk_fma_f32 v[150:151], v[160:161], v[44:45], v[150:151] op_sel_hi:[0,1,1]
	v_pk_add_f32 v[146:147], v[146:147], v[14:15]
	v_pk_fma_f32 v[14:15], v[2:3], v[12:13], v[202:203] op_sel_hi:[1,0,1]
	v_pk_fma_f32 v[12:13], v[0:1], v[12:13], v[204:205] op_sel_hi:[1,0,1]
	v_pk_fma_f32 v[2:3], v[2:3], v[148:149], v[220:221] op_sel_hi:[1,0,1]
	v_pk_fma_f32 v[0:1], v[0:1], v[148:149], v[218:219] op_sel_hi:[1,0,1]
	v_mov_b32_e32 v148, v201
	v_pk_add_f32 v[142:143], v[150:151], v[142:143]
	v_pk_mul_f32 v[150:151], v[148:149], v[134:135] op_sel_hi:[0,1]
	v_pk_mul_f32 v[148:149], v[148:149], v[132:133] op_sel_hi:[0,1]
	v_mov_b32_e32 v158, v161
	v_pk_fma_f32 v[160:161], v[158:159], v[48:49], v[148:149] op_sel_hi:[0,1,1]
	v_pk_fma_f32 v[148:149], v[158:159], v[50:51], v[150:151] op_sel_hi:[0,1,1]
	v_pk_add_f32 v[148:149], v[148:149], v[146:147]
	v_pk_add_f32 v[146:147], v[160:161], v[142:143]
	global_store_dwordx4 v[144:145], v[146:149], off offset:3072 nt
	s_cbranch_scc0 .LBB0_316
	v_lshlrev_b32_e32 v34, 13, v195
	v_add3_u32 v34, 0, v34, v152
	ds_write_b128 v34, v[24:27] offset:12544
	ds_write_b128 v34, v[4:7] offset:13568
	ds_write_b128 v34, v[8:11] offset:14592
	ds_write_b128 v34, v[12:15] offset:15616
	ds_write_b128 v34, v[28:31] offset:16640
	ds_write_b128 v34, v[16:19] offset:17664
	ds_write_b128 v34, v[20:23] offset:18688
	ds_write_b128 v34, v[0:3] offset:19712
	v_ashrrev_i32_e32 v0, 8, v175
	v_lshl_add_u32 v15, v32, 2, 0
	v_lshl_add_u32 v6, v0, 12, v15
	s_waitcnt lgkmcnt(0)
	s_barrier
	ds_read2st64_b32 v[2:3], v6 offset0:49 offset1:81
	ds_read2st64_b32 v[4:5], v6 offset0:113 offset1:145
	v_lshlrev_b32_e32 v24, 2, v0
	v_or_b32_e32 v18, 1, v24
	v_add_u32_e32 v7, 0x3100, v6
	s_waitcnt lgkmcnt(0)
	v_add_f32_e32 v2, 0, v2
	v_add_f32_e32 v8, v2, v3
	ds_read2st64_b32 v[2:3], v6 offset0:177 offset1:209
	v_add_f32_e32 v4, v8, v4
	v_add_f32_e32 v4, v4, v5
	v_cvt_f32_i32_e32 v5, v18
	v_lshlrev_b32_e32 v1, 16, v194
	s_waitcnt lgkmcnt(0)
	v_add_f32_e32 v2, v4, v2
	ds_read_b32 v4, v6 offset:61696
	ds_read_b32 v6, v7 offset:57344
	v_mul_f32_e32 v5, v33, v5
	v_exp_f32_e32 v5, v5
	v_add_f32_e32 v2, v2, v3
	s_waitcnt lgkmcnt(0)
	v_add_f32_e32 v2, v2, v4
	v_add_f32_e32 v2, v2, v6
	v_mul_f32_e32 v19, v5, v2
	v_lshlrev_b32_e32 v2, 7, v0
	v_cmp_lt_i32_e32 vcc, -1, v0
	v_add_u32_e32 v9, 0, v2
	s_and_saveexec_b64 s[10:11], vcc
	v_readlane_b32 s80, v254, 21
	v_readlane_b32 s84, v254, 51
	v_readlane_b32 s81, v254, 22
	v_readlane_b32 s85, v254, 52
	s_mov_b32 s96, s8
	s_cbranch_execz .LBB0_319
	ds_read_b32 v2, v9 offset:12288
	s_waitcnt lgkmcnt(0)
	v_fmac_f32_e32 v19, v2, v1

.LBB0_789:
	v_readlane_b32 s6, v253, 24
	v_readlane_b32 s7, v253, 25
	v_cvt_f32_u32_e32 v1, v2
	v_sub_u32_e32 v4, 0, v2
	v_rcp_iflag_f32_e32 v1, v1
	s_nop 1
	global_atomic_add v3, v153, v154, s[6:7] sc0
	v_mul_f32_e32 v1, 0x4f7ffffe, v1
	v_cvt_u32_f32_e32 v1, v1
	v_mul_lo_u32 v4, v4, v1
	v_mul_hi_u32 v4, v1, v4
	v_add_u32_e32 v1, v1, v4
	s_waitcnt vmcnt(0)
	v_mul_hi_u32 v1, v3, v1
	v_mul_lo_u32 v4, v1, v2
	v_sub_u32_e32 v4, v3, v4
	v_add_u32_e32 v5, 1, v1
	v_cmp_ge_u32_e32 vcc, v4, v2
	v_add_u32_e32 v3, 1, v3
	s_nop 0
	v_cndmask_b32_e32 v1, v1, v5, vcc
	v_sub_u32_e32 v5, v4, v2
	v_cndmask_b32_e32 v4, v4, v5, vcc
	v_add_u32_e32 v5, 1, v1
	v_cmp_ge_u32_e32 vcc, v4, v2
	s_nop 1
	v_cndmask_b32_e32 v1, v1, v5, vcc
	v_mul_lo_u32 v4, v2, v1
	v_add_u32_e32 v2, v4, v2
	v_cmp_ne_u32_e32 vcc, v3, v2
	s_and_saveexec_b64 s[6:7], vcc
	s_xor_b64 s[6:7], exec, s[6:7]
	s_cbranch_execz .LBB0_803
	v_readlane_b32 s8, v253, 30
	v_readlane_b32 s9, v253, 31
	s_waitcnt lgkmcnt(0)
	s_nop 3
	global_load_dword v0, v153, s[8:9] sc1
	s_waitcnt vmcnt(0)
	v_cmp_eq_u32_e32 vcc, v0, v1
	s_and_saveexec_b64 s[8:9], vcc
	s_cbranch_execz .LBB0_802
	s_mov_b32 s0, 1
	s_mov_b64 s[10:11], 0
	s_branch .LBB0_793

.LBB0_795:
	v_readlane_b32 s14, v253, 30
	v_readlane_b32 s15, v253, 31
	s_add_i32 s0, s0, 1
	s_mov_b64 s[16:17], -1
	s_nop 2
	global_load_dword v0, v153, s[14:15] sc1
	s_waitcnt vmcnt(0)
	v_cmp_ne_u32_e32 vcc, v0, v1
	s_orn2_b64 s[14:15], vcc, exec
	s_branch .LBB0_792
